# NSA flash loops: cross-half row max / row sum via v_permlane32_swap instead of ds_bpermute + LDS wait
# speedup vs baseline: 1.0027x; 1.0027x over previous
; DI int crow(int reg, int h) { return (reg & 3) + 8 * (reg >> 2) + 4 * h; }
; #define MFMA32(a, b, c) __builtin_amdgcn_mfma_f32_32x32x16_bf16((a), (b), (c), 0, 0, 0)
; template <int MODE>
; DI void nsa_flash(const bf16_t* kbase, const bf16_t* vbase, int j0, int j1, int t, unsigned selmask, const bf16x8 (&qf)[4],
;                   f32x16 (&o)[2], float& lsum, bf16_t* Ks, bf16_t* VTs, int tid, int r, int hh) {
;     ...
;     __syncthreads();
;     *(u32x4*)(Ks + kkey * 72 + kdc * 8) = kreg;
; #pragma unroll
;     for (int e = 0; e < 4; ++e) { VTs[(dc * 8 + 2 * e) * 136 + key] = (bf16_t)(vreg[e] & 0xffffu); VTs[(dc * 8 + 2 * e + 1) * 136 + key] = (bf16_t)(vreg[e] >> 16); }
;     __syncthreads();
;     if (j < j1) { kreg = *(const u32x4*)(kbase + (size_t)((j + 1) * 64 + kkey) * LDP0 + kdc * 8); vreg = *(const u32x4*)(vbase + (size_t)((j + 1) * 64 + key) * LDP0 + dc * 8); }
;     const bool rowsel = (MODE == 1) ? (((selmask >> j) & 1u) != 0u) : true;
;     const bool needmask = (j == j1) || (MODE == 2 && j + 8 == j1);
;     f32x16 x[2]; float mx = NEGF;
; #pragma unroll
;     for (int sub = 0; sub < 2; ++sub) { x[sub] = zero16();
; #pragma unroll
;       for (int kk = 0; kk < 4; ++kk) x[sub] = MFMA32(*(const bf16x8*)(Ks + (sub * 32 + r) * 72 + kk * 16 + 8 * hh), qf[kk], x[sub]); }
;     if (needmask) {
; #pragma unroll
;       for (int sub = 0; sub < 2; ++sub)
; #pragma unroll
;         for (int i = 0; i < 16; ++i) { const int kp = j * 64 + sub * 32 + crow(i, hh);
;           bool ok = (kp <= t); if (MODE == 2) ok = ok && (t - kp < 512);
;           x[sub][i] = ok ? x[sub][i] : NEGF; }
;     }
; #pragma unroll
;     for (int sub = 0; sub < 2; ++sub)
; #pragma unroll
;       for (int i = 0; i < 16; ++i) mx = fmaxf(mx, x[sub][i]);
.LBB0_630:
	v_mad_i64_i32 v[32:33], s[4:5], v130, s97, v[94:95]
	v_mov_b32_e32 v133, v121
	s_waitcnt lgkmcnt(0)
	s_barrier
	s_waitcnt vmcnt(1)
	ds_write_b128 v125, v[84:87]
	s_waitcnt vmcnt(0)
	ds_write_b16 v117, v80 offset:18432
	ds_write_b16_d16_hi v118, v80 offset:18704
	ds_write_b16 v117, v81 offset:18976
	ds_write_b16_d16_hi v118, v81 offset:19248
	ds_write_b16 v117, v82 offset:19520
	ds_write_b16_d16_hi v118, v82 offset:19792
	ds_write_b16 v117, v83 offset:20064
	ds_write_b16_d16_hi v118, v83 offset:20336
	s_waitcnt lgkmcnt(0)
	s_barrier
	global_load_dwordx4 v[84:87], v[32:33], off
	v_mad_i64_i32 v[32:33], s[4:5], v131, s97, v[96:97]
	v_add_u32_e32 v121, v111, v114
	global_load_dwordx4 v[80:83], v[32:33], off
	ds_read_b128 v[32:35], v121
	ds_read_b128 v[36:39], v121 offset:32
	s_waitcnt lgkmcnt(1)
	v_mfma_f32_32x32x16_bf16 v[48:63], v[32:35], v[64:67], 0
	ds_read_b128 v[32:35], v121 offset:64
	ds_read_b128 v[134:137], v121 offset:4640
	v_add_u32_e32 v131, 64, v131
	v_add_u32_e32 v130, 64, v130
	s_waitcnt lgkmcnt(2)
	v_mfma_f32_32x32x16_bf16 v[48:63], v[36:39], v[68:71], v[48:63]
	s_waitcnt lgkmcnt(1)
	v_mfma_f32_32x32x16_bf16 v[48:63], v[32:35], v[72:75], v[48:63]
	ds_read_b128 v[32:35], v121 offset:96
	s_waitcnt lgkmcnt(0)
	v_mfma_f32_32x32x16_bf16 v[48:63], v[32:35], v[76:79], v[48:63]
	ds_read_b128 v[32:35], v121 offset:4608
	s_waitcnt lgkmcnt(0)
	v_mfma_f32_32x32x16_bf16 v[32:47], v[32:35], v[64:67], 0
	v_mfma_f32_32x32x16_bf16 v[32:47], v[134:137], v[68:71], v[32:47]
	ds_read_b128 v[134:137], v121 offset:4672
	s_waitcnt lgkmcnt(0)
	v_mfma_f32_32x32x16_bf16 v[32:47], v[134:137], v[72:75], v[32:47]
	ds_read_b128 v[134:137], v121 offset:4704
	v_lshrrev_b32_e32 v121, s2, v122
	v_and_b32_e32 v121, 1, v121
	v_cmp_eq_u32_e32 vcc, 1, v121
	s_nop 0
	v_max3_f32 v121, v48, s3, v49
	v_max3_f32 v121, v121, v50, v51
	v_max3_f32 v121, v121, v52, v53
	s_waitcnt lgkmcnt(0)
; #define MFMA32(a, b, c) __builtin_amdgcn_mfma_f32_32x32x16_bf16((a), (b), (c), 0, 0, 0)
; template <int MODE>
; DI void nsa_flash(const bf16_t* kbase, const bf16_t* vbase, int j0, int j1, int t, unsigned selmask, const bf16x8 (&qf)[4],
;                   f32x16 (&o)[2], float& lsum, bf16_t* Ks, bf16_t* VTs, int tid, int r, int hh) {
;     ...
; #pragma unroll
;     for (int sub = 0; sub < 2; ++sub)
; #pragma unroll
;       for (int i = 0; i < 16; ++i) mx = fmaxf(mx, x[sub][i]);
;     mx = fmaxf(mx, __shfl_xor(mx, 32));
;     mx = rowsel ? fmaxf(m, mx) : m;
;     const float alpha = __builtin_amdgcn_exp2f(m - mx); m = mx;
;     const float mexp = (rowsel && mx > -1e29f) ? mx : 1e30f;
;     float ps = 0.f;
; #pragma unroll
;     for (int sub = 0; sub < 2; ++sub)
; #pragma unroll
;       for (int i = 0; i < 16; ++i) { const float pv = __builtin_amdgcn_exp2f(x[sub][i] - mexp); x[sub][i] = pv; ps += pv; }
;     ps += __shfl_xor(ps, 32);
;     lsum = lsum * alpha + ps;
; #pragma unroll
;     for (int i = 0; i < 16; ++i) { o[0][i] *= alpha; o[1][i] *= alpha; }
; #pragma unroll
;     for (int sub = 0; sub < 2; ++sub)
; #pragma unroll
;       for (int s2 = 0; s2 < 2; ++s2) {
;         const bf16x8 pb = pack8(x[sub][8 * s2], x[sub][8 * s2 + 1], x[sub][8 * s2 + 2], x[sub][8 * s2 + 3], x[sub][8 * s2 + 4], x[sub][8 * s2 + 5], x[sub][8 * s2 + 6], x[sub][8 * s2 + 7]);
; #pragma unroll
;         for (int dt = 0; dt < 2; ++dt) { const bf16_t* vp = VTs + (dt * 32 + r) * 136 + sub * 32 + 16 * s2 + 4 * hh;
;           const s16x4 lo = *(const s16x4*)vp, hi = *(const s16x4*)(vp + 8);
;           const bf16x8 va = __builtin_shufflevector(lo, hi, 0, 1, 2, 3, 4, 5, 6, 7);
;           o[dt] = MFMA32(va, pb, o[dt]); } }
;   }
	v_mfma_f32_32x32x16_bf16 v[32:47], v[134:137], v[76:79], v[32:47]
	ds_read2_b64 v[228:231], v251 offset0:64 offset1:66
	ds_read2_b64 v[232:235], v251 offset0:68 offset1:70
	ds_read2_b64 v[236:239], v250 offset0:8 offset1:10
	ds_read2_b64 v[240:243], v251 offset0:72 offset1:74
	ds_read2_b64 v[244:247], v250 offset0:12 offset1:14
	v_max3_f32 v121, v121, v54, v55
	v_max3_f32 v121, v121, v56, v57
	v_max3_f32 v121, v121, v58, v59
	v_max3_f32 v121, v121, v60, v61
	v_max3_f32 v121, v121, v62, v63
	s_add_i32 s2, s2, 1
	s_nop 5
	v_max3_f32 v121, v121, v32, v33
	v_max3_f32 v121, v121, v34, v35
	v_max3_f32 v121, v121, v36, v37
	v_max3_f32 v121, v121, v38, v39
	v_max3_f32 v121, v121, v40, v41
	v_max3_f32 v121, v121, v42, v43
	v_max3_f32 v121, v121, v44, v45
	v_max3_f32 v121, v121, v46, v47
	v_mov_b32_e32 v129, v121
	s_nop 1
	v_permlane32_swap_b32_e32 v121, v129
	v_max3_f32 v121, v132, v121, v129
	v_cndmask_b32_e32 v129, v132, v121, vcc
	v_cmp_lt_f32_e64 s[6:7], s12, v129
	s_and_b64 vcc, vcc, s[6:7]
	v_cndmask_b32_e32 v121, v202, v121, vcc
	v_sub_f32_e32 v48, v48, v121
	v_exp_f32_e32 v134, v48
	v_sub_f32_e32 v49, v49, v121
	v_exp_f32_e32 v135, v49
	v_sub_f32_e32 v49, v50, v121
	v_exp_f32_e32 v136, v49
	v_sub_f32_e32 v49, v51, v121
	v_exp_f32_e32 v137, v49
	v_sub_f32_e32 v49, v52, v121
	v_add_f32_e32 v48, 0, v134
	v_exp_f32_e32 v138, v49
	v_sub_f32_e32 v49, v53, v121
	v_add_f32_e32 v48, v135, v48
	v_exp_f32_e32 v139, v49
	v_sub_f32_e32 v49, v54, v121
	v_add_f32_e32 v48, v136, v48
	v_exp_f32_e32 v140, v49
	v_sub_f32_e32 v49, v55, v121
	v_add_f32_e32 v48, v137, v48
	v_exp_f32_e32 v141, v49
	v_add_f32_e32 v48, v138, v48
	v_add_f32_e32 v48, v139, v48
	v_add_f32_e32 v48, v140, v48
	v_add_f32_e32 v49, v141, v48
	v_sub_f32_e32 v48, v56, v121
	v_exp_f32_e32 v48, v48
	v_sub_f32_e32 v56, v63, v121
	v_exp_f32_e32 v56, v56
	v_sub_f32_e32 v32, v32, v121
	v_add_f32_e32 v50, v48, v49
	v_sub_f32_e32 v49, v57, v121
	v_exp_f32_e32 v49, v49
	v_sub_f32_e32 v33, v33, v121
	v_sub_f32_e32 v132, v132, v129
	v_cmp_eq_u32_e32 vcc, s2, v100
	v_add_f32_e32 v51, v49, v50
	v_sub_f32_e32 v50, v58, v121
	v_exp_f32_e32 v50, v50
	s_or_b64 s[10:11], vcc, s[10:11]
	v_add_f32_e32 v52, v50, v51
	v_sub_f32_e32 v51, v59, v121
	v_exp_f32_e32 v51, v51
	s_nop 0
	v_add_f32_e32 v53, v51, v52
	v_sub_f32_e32 v52, v60, v121
	v_exp_f32_e32 v52, v52
	s_nop 0
	v_add_f32_e32 v54, v52, v53
	v_sub_f32_e32 v53, v61, v121
	v_exp_f32_e32 v53, v53
	s_nop 0
	v_add_f32_e32 v55, v53, v54
	v_sub_f32_e32 v54, v62, v121
	v_exp_f32_e32 v54, v54
	s_nop 0
	v_add_f32_e32 v55, v54, v55
	v_add_f32_e32 v57, v56, v55
	v_exp_f32_e32 v55, v32
	s_nop 0
	v_add_f32_e32 v32, v55, v57
	v_exp_f32_e32 v57, v33
	v_sub_f32_e32 v33, v34, v121
	v_exp_f32_e32 v58, v33
	v_sub_f32_e32 v33, v35, v121
	v_exp_f32_e32 v59, v33
	v_sub_f32_e32 v33, v36, v121
	v_exp_f32_e32 v36, v33
	v_sub_f32_e32 v33, v37, v121
	v_add_f32_e32 v32, v57, v32
	v_exp_f32_e32 v37, v33
	v_sub_f32_e32 v33, v38, v121
	v_add_f32_e32 v32, v58, v32
	v_exp_f32_e32 v38, v33
	v_sub_f32_e32 v33, v39, v121
	v_add_f32_e32 v32, v59, v32
	v_exp_f32_e32 v60, v33
	v_sub_f32_e32 v33, v40, v121
	v_add_f32_e32 v32, v36, v32
	v_exp_f32_e32 v39, v33
	v_sub_f32_e32 v33, v41, v121
	v_add_f32_e32 v32, v37, v32
	v_exp_f32_e32 v40, v33
	v_sub_f32_e32 v33, v42, v121
	v_add_f32_e32 v32, v38, v32
	v_exp_f32_e32 v41, v33
	v_sub_f32_e32 v33, v43, v121
	v_add_f32_e32 v32, v60, v32
	v_exp_f32_e32 v42, v33
	v_sub_f32_e32 v33, v44, v121
	v_add_f32_e32 v32, v39, v32
	v_exp_f32_e32 v43, v33
	v_sub_f32_e32 v33, v45, v121
	v_add_f32_e32 v32, v40, v32
	v_exp_f32_e32 v44, v33
	v_sub_f32_e32 v33, v46, v121
	v_add_f32_e32 v32, v41, v32
	v_exp_f32_e32 v45, v33
	v_sub_f32_e32 v33, v47, v121
	v_add_f32_e32 v32, v42, v32
	v_exp_f32_e32 v46, v33
	v_add_f32_e32 v32, v43, v32
	v_add_f32_e32 v32, v44, v32
	v_add_f32_e32 v32, v45, v32
	v_add_f32_e32 v33, v46, v32
	v_mov_b32_e32 v34, v33
	v_exp_f32_e32 v32, v132
	v_add_u32_e32 v47, v112, v113
	v_add_u32_e32 v61, 0x4800, v47
	v_cvt_pk_bf16_f32 v35, v140, v141
	s_nop 1
	v_permlane32_swap_b32_e32 v33, v34
	v_add_f32_e32 v121, v33, v34
	v_fmac_f32_e32 v121, v133, v32
	v_pk_mul_f32 v[0:1], v[0:1], v[32:33] op_sel_hi:[1,0]
	v_pk_mul_f32 v[16:17], v[16:17], v[32:33] op_sel_hi:[1,0]
	v_pk_mul_f32 v[2:3], v[2:3], v[32:33] op_sel_hi:[1,0]
	v_pk_mul_f32 v[18:19], v[18:19], v[32:33] op_sel_hi:[1,0]
	v_pk_mul_f32 v[4:5], v[4:5], v[32:33] op_sel_hi:[1,0]
	v_pk_mul_f32 v[20:21], v[20:21], v[32:33] op_sel_hi:[1,0]
	v_pk_mul_f32 v[6:7], v[6:7], v[32:33] op_sel_hi:[1,0]
	v_pk_mul_f32 v[22:23], v[22:23], v[32:33] op_sel_hi:[1,0]
	v_pk_mul_f32 v[8:9], v[8:9], v[32:33] op_sel_hi:[1,0]
	v_pk_mul_f32 v[24:25], v[24:25], v[32:33] op_sel_hi:[1,0]
	v_pk_mul_f32 v[10:11], v[10:11], v[32:33] op_sel_hi:[1,0]
	v_pk_mul_f32 v[26:27], v[26:27], v[32:33] op_sel_hi:[1,0]
	v_pk_mul_f32 v[12:13], v[12:13], v[32:33] op_sel_hi:[1,0]
	v_pk_mul_f32 v[28:29], v[28:29], v[32:33] op_sel_hi:[1,0]
	v_pk_mul_f32 v[14:15], v[14:15], v[32:33] op_sel_hi:[1,0]
	v_pk_mul_f32 v[30:31], v[30:31], v[32:33] op_sel_hi:[1,0]
	v_cvt_pk_bf16_f32 v32, v134, v135
	v_cvt_pk_bf16_f32 v33, v136, v137
	v_cvt_pk_bf16_f32 v34, v138, v139
	ds_read2_b64 v[132:135], v61 offset1:2
	ds_read2_b64 v[136:139], v61 offset0:4 offset1:6
	v_add_u32_e32 v47, 0x6800, v47
	s_waitcnt lgkmcnt(1)
	v_mfma_f32_32x32x16_bf16 v[0:15], v[132:135], v[32:35], v[0:15]
	s_waitcnt lgkmcnt(0)
	v_mfma_f32_32x32x16_bf16 v[16:31], v[228:231], v[32:35], v[16:31]
	v_cvt_pk_bf16_f32 v32, v48, v49
	v_cvt_pk_bf16_f32 v33, v50, v51
	v_cvt_pk_bf16_f32 v34, v52, v53
	v_cvt_pk_bf16_f32 v35, v54, v56
	v_mov_b32_e32 v132, v129
	s_waitcnt lgkmcnt(0)
	v_mfma_f32_32x32x16_bf16 v[16:31], v[232:235], v[32:35], v[16:31]
	v_mfma_f32_32x32x16_bf16 v[0:15], v[136:139], v[32:35], v[0:15]
	v_cvt_pk_bf16_f32 v32, v55, v57
	v_cvt_pk_bf16_f32 v33, v58, v59
	v_cvt_pk_bf16_f32 v34, v36, v37
	v_cvt_pk_bf16_f32 v35, v38, v60
	s_waitcnt lgkmcnt(0)
	s_nop 0
	v_mfma_f32_32x32x16_bf16 v[0:15], v[236:239], v[32:35], v[0:15]
	s_waitcnt lgkmcnt(0)
	v_mfma_f32_32x32x16_bf16 v[16:31], v[240:243], v[32:35], v[16:31]
	v_cvt_pk_bf16_f32 v32, v39, v40
	v_cvt_pk_bf16_f32 v33, v41, v42
	v_cvt_pk_bf16_f32 v34, v43, v44
	v_cvt_pk_bf16_f32 v35, v45, v46
	s_waitcnt lgkmcnt(0)
	s_nop 0
	v_mfma_f32_32x32x16_bf16 v[0:15], v[244:247], v[32:35], v[0:15]
	ds_read2_b64 v[36:39], v47 offset0:76 offset1:78
	s_waitcnt lgkmcnt(0)
	v_mfma_f32_32x32x16_bf16 v[16:31], v[36:39], v[32:35], v[16:31]
	s_andn2_b64 exec, exec, s[10:11]
	s_cbranch_execnz .LBB0_630
	s_mov_b32 s90, 0xefa18f08
	s_or_b64 exec, exec, s[10:11]

; #define MFMA32(a, b, c) __builtin_amdgcn_mfma_f32_32x32x16_bf16((a), (b), (c), 0, 0, 0)
; template <int MODE>
; DI void nsa_flash(const bf16_t* kbase, const bf16_t* vbase, int j0, int j1, int t, unsigned selmask, const bf16x8 (&qf)[4],
;                   f32x16 (&o)[2], float& lsum, bf16_t* Ks, bf16_t* VTs, int tid, int r, int hh) {
;     ...
; #pragma unroll
;     for (int sub = 0; sub < 2; ++sub)
; #pragma unroll
;       for (int i = 0; i < 16; ++i) mx = fmaxf(mx, x[sub][i]);
;     mx = fmaxf(mx, __shfl_xor(mx, 32));
;     mx = rowsel ? fmaxf(m, mx) : m;
;     const float alpha = __builtin_amdgcn_exp2f(m - mx); m = mx;
;     const float mexp = (rowsel && mx > -1e29f) ? mx : 1e30f;
;     float ps = 0.f;
; #pragma unroll
;     for (int sub = 0; sub < 2; ++sub)
; #pragma unroll
;       for (int i = 0; i < 16; ++i) { const float pv = __builtin_amdgcn_exp2f(x[sub][i] - mexp); x[sub][i] = pv; ps += pv; }
;     ps += __shfl_xor(ps, 32);
;     lsum = lsum * alpha + ps;
; #pragma unroll
;     for (int i = 0; i < 16; ++i) { o[0][i] *= alpha; o[1][i] *= alpha; }
; #pragma unroll
;     for (int sub = 0; sub < 2; ++sub)
; #pragma unroll
;       for (int s2 = 0; s2 < 2; ++s2) {
;         const bf16x8 pb = pack8(x[sub][8 * s2], x[sub][8 * s2 + 1], x[sub][8 * s2 + 2], x[sub][8 * s2 + 3], x[sub][8 * s2 + 4], x[sub][8 * s2 + 5], x[sub][8 * s2 + 6], x[sub][8 * s2 + 7]);
; #pragma unroll
;         for (int dt = 0; dt < 2; ++dt) { const bf16_t* vp = VTs + (dt * 32 + r) * 136 + sub * 32 + 16 * s2 + 4 * hh;
;           const s16x4 lo = *(const s16x4*)vp, hi = *(const s16x4*)(vp + 8);
;           const bf16x8 va = __builtin_shufflevector(lo, hi, 0, 1, 2, 3, 4, 5, 6, 7);
;           o[dt] = MFMA32(va, pb, o[dt]); } }
;   }
.LBB0_636:
	s_or_b64 exec, exec, s[2:3]
	s_and_b64 s[2:3], exec, vcc
	s_or_b64 s[12:13], s[2:3], s[12:13]
	s_mov_b32 s2, 0xf149f2ca
	v_max3_f32 v109, v48, s2, v49
	v_max3_f32 v109, v109, v50, v51
	v_max3_f32 v109, v109, v52, v53
	v_max3_f32 v109, v109, v54, v55
	v_max3_f32 v109, v109, v56, v57
	v_max3_f32 v109, v109, v58, v59
	v_max3_f32 v109, v109, v60, v61
	v_max3_f32 v109, v109, v62, v63
	v_max3_f32 v109, v109, v32, v33
	v_max3_f32 v109, v109, v34, v35
	v_max3_f32 v109, v109, v36, v37
	v_max3_f32 v109, v109, v38, v39
	v_max3_f32 v109, v109, v40, v41
	v_max3_f32 v109, v109, v42, v43
	v_max3_f32 v109, v109, v44, v45
	v_max3_f32 v109, v109, v46, v47
	v_mov_b32_e32 v112, v109
	v_add_u32_e32 v97, 1, v97
	v_add_u32_e32 v107, 64, v107
	s_waitcnt lgkmcnt(0)
	s_nop 1
	v_permlane32_swap_b32_e32 v109, v112
	v_max3_f32 v109, v111, v109, v112
	v_cmp_lt_f32_e32 vcc, s90, v109
	v_sub_f32_e32 v111, v111, v109
	s_nop 0
	v_cndmask_b32_e32 v112, v202, v109, vcc
	v_sub_f32_e32 v48, v48, v112
	v_exp_f32_e32 v113, v48
	v_sub_f32_e32 v49, v49, v112
	v_exp_f32_e32 v114, v49
	v_sub_f32_e32 v49, v50, v112
	v_exp_f32_e32 v119, v49
	v_sub_f32_e32 v49, v51, v112
	v_exp_f32_e32 v51, v49
	v_sub_f32_e32 v49, v52, v112
	v_add_f32_e32 v48, 0, v113
	v_exp_f32_e32 v52, v49
	v_sub_f32_e32 v49, v53, v112
	v_add_f32_e32 v48, v114, v48
	v_exp_f32_e32 v53, v49
	v_sub_f32_e32 v49, v54, v112
	v_add_f32_e32 v48, v119, v48
	v_exp_f32_e32 v54, v49
	v_sub_f32_e32 v49, v55, v112
	v_add_f32_e32 v48, v51, v48
	v_exp_f32_e32 v55, v49
	v_add_f32_e32 v48, v52, v48
	v_add_f32_e32 v48, v53, v48
	v_add_f32_e32 v48, v54, v48
	v_add_f32_e32 v49, v55, v48
	v_sub_f32_e32 v48, v56, v112
	v_exp_f32_e32 v48, v48
	v_sub_f32_e32 v32, v32, v112
	v_sub_f32_e32 v33, v33, v112
	v_add_f32_e32 v50, v48, v49
	v_sub_f32_e32 v49, v57, v112
	v_exp_f32_e32 v49, v49
	v_sub_f32_e32 v57, v59, v112
	v_exp_f32_e32 v57, v57
	v_sub_f32_e32 v59, v61, v112
	v_add_f32_e32 v56, v49, v50
	v_sub_f32_e32 v50, v58, v112
	v_exp_f32_e32 v50, v50
	v_sub_f32_e32 v58, v60, v112
	v_exp_f32_e32 v58, v58
	v_exp_f32_e32 v59, v59
	v_sub_f32_e32 v60, v62, v112
	v_add_f32_e32 v56, v50, v56
	v_exp_f32_e32 v60, v60
	v_sub_f32_e32 v61, v63, v112
	v_add_f32_e32 v56, v57, v56
	v_exp_f32_e32 v61, v61
	v_add_f32_e32 v56, v58, v56
	v_exp_f32_e32 v62, v32
	v_add_f32_e32 v56, v59, v56
	v_add_f32_e32 v56, v60, v56
	v_add_f32_e32 v56, v61, v56
	v_add_f32_e32 v32, v62, v56
	v_exp_f32_e32 v56, v33
	v_sub_f32_e32 v33, v34, v112
	v_exp_f32_e32 v63, v33
	v_sub_f32_e32 v33, v35, v112
	v_exp_f32_e32 v120, v33
	v_sub_f32_e32 v33, v36, v112
	v_exp_f32_e32 v121, v33
	v_sub_f32_e32 v33, v37, v112
	v_add_f32_e32 v32, v56, v32
	v_exp_f32_e32 v37, v33
	v_sub_f32_e32 v33, v38, v112
	v_add_f32_e32 v32, v63, v32
	v_exp_f32_e32 v122, v33
	v_sub_f32_e32 v33, v39, v112
	v_add_f32_e32 v32, v120, v32
	v_exp_f32_e32 v123, v33
	v_sub_f32_e32 v33, v40, v112
	v_add_f32_e32 v32, v121, v32
	v_exp_f32_e32 v124, v33
	v_sub_f32_e32 v33, v41, v112
	v_add_f32_e32 v32, v37, v32
	v_exp_f32_e32 v125, v33
	v_sub_f32_e32 v33, v42, v112
	v_add_f32_e32 v32, v122, v32
	v_exp_f32_e32 v126, v33
	v_sub_f32_e32 v33, v43, v112
	v_add_f32_e32 v32, v123, v32
	v_exp_f32_e32 v127, v33
	v_sub_f32_e32 v33, v44, v112
	v_add_f32_e32 v32, v124, v32
	v_exp_f32_e32 v128, v33
	v_sub_f32_e32 v33, v45, v112
	v_add_f32_e32 v32, v125, v32
	v_exp_f32_e32 v129, v33
	v_sub_f32_e32 v33, v46, v112
	v_add_f32_e32 v32, v126, v32
	v_exp_f32_e32 v46, v33
	v_sub_f32_e32 v33, v47, v112
	v_add_f32_e32 v32, v127, v32
	v_exp_f32_e32 v47, v33
	v_add_f32_e32 v32, v128, v32
	v_add_f32_e32 v32, v129, v32
	v_add_f32_e32 v32, v46, v32
	v_add_f32_e32 v33, v47, v32
	v_mov_b32_e32 v34, v33
	v_exp_f32_e32 v32, v111
	ds_read2_b64 v[38:41], v95 offset1:2
	ds_read2_b64 v[42:45], v95 offset0:4 offset1:6
	v_cvt_pk_bf16_f32 v35, v54, v55
	v_mov_b32_e32 v111, v109
	s_waitcnt lgkmcnt(2)
	s_nop 1
	v_permlane32_swap_b32_e32 v33, v34
	v_add_f32_e32 v36, v33, v34
	v_fmac_f32_e32 v36, v110, v32
	v_pk_mul_f32 v[0:1], v[0:1], v[32:33] op_sel_hi:[1,0]
	v_pk_mul_f32 v[16:17], v[16:17], v[32:33] op_sel_hi:[1,0]
	v_pk_mul_f32 v[2:3], v[2:3], v[32:33] op_sel_hi:[1,0]
	v_pk_mul_f32 v[18:19], v[18:19], v[32:33] op_sel_hi:[1,0]
	v_pk_mul_f32 v[4:5], v[4:5], v[32:33] op_sel_hi:[1,0]
	v_pk_mul_f32 v[20:21], v[20:21], v[32:33] op_sel_hi:[1,0]
	v_pk_mul_f32 v[6:7], v[6:7], v[32:33] op_sel_hi:[1,0]
	v_pk_mul_f32 v[22:23], v[22:23], v[32:33] op_sel_hi:[1,0]
	v_pk_mul_f32 v[8:9], v[8:9], v[32:33] op_sel_hi:[1,0]
	v_pk_mul_f32 v[24:25], v[24:25], v[32:33] op_sel_hi:[1,0]
	v_pk_mul_f32 v[10:11], v[10:11], v[32:33] op_sel_hi:[1,0]
	v_pk_mul_f32 v[26:27], v[26:27], v[32:33] op_sel_hi:[1,0]
	v_pk_mul_f32 v[12:13], v[12:13], v[32:33] op_sel_hi:[1,0]
	v_pk_mul_f32 v[28:29], v[28:29], v[32:33] op_sel_hi:[1,0]
	v_pk_mul_f32 v[14:15], v[14:15], v[32:33] op_sel_hi:[1,0]
	v_pk_mul_f32 v[30:31], v[30:31], v[32:33] op_sel_hi:[1,0]
	v_cvt_pk_bf16_f32 v32, v113, v114
	v_cvt_pk_bf16_f32 v33, v119, v51
	v_cvt_pk_bf16_f32 v34, v52, v53
	v_mov_b32_e32 v110, v36
	s_waitcnt lgkmcnt(1)
	v_mfma_f32_32x32x16_bf16 v[0:15], v[38:41], v[32:35], v[0:15]
	ds_read2_b64 v[38:41], v96 offset0:64 offset1:66
	s_waitcnt lgkmcnt(0)
	v_mfma_f32_32x32x16_bf16 v[16:31], v[38:41], v[32:35], v[16:31]
	ds_read2_b64 v[38:41], v96 offset0:68 offset1:70
	v_cvt_pk_bf16_f32 v32, v48, v49
	v_cvt_pk_bf16_f32 v33, v50, v57
	v_cvt_pk_bf16_f32 v34, v58, v59
	v_cvt_pk_bf16_f32 v35, v60, v61
	s_waitcnt lgkmcnt(0)
	s_nop 0
	v_mfma_f32_32x32x16_bf16 v[16:31], v[38:41], v[32:35], v[16:31]
	ds_read2_b64 v[38:41], v95 offset0:8 offset1:10
	v_mfma_f32_32x32x16_bf16 v[0:15], v[42:45], v[32:35], v[0:15]
	v_cvt_pk_bf16_f32 v32, v62, v56
	v_cvt_pk_bf16_f32 v33, v63, v120
	v_cvt_pk_bf16_f32 v34, v121, v37
	v_cvt_pk_bf16_f32 v35, v122, v123
	s_waitcnt lgkmcnt(0)
	s_nop 0
	v_mfma_f32_32x32x16_bf16 v[0:15], v[38:41], v[32:35], v[0:15]
	ds_read2_b64 v[38:41], v96 offset0:72 offset1:74
	s_waitcnt lgkmcnt(0)
	v_mfma_f32_32x32x16_bf16 v[16:31], v[38:41], v[32:35], v[16:31]
	ds_read2_b64 v[38:41], v95 offset0:12 offset1:14
	v_cvt_pk_bf16_f32 v32, v124, v125
	v_cvt_pk_bf16_f32 v33, v126, v127
	v_cvt_pk_bf16_f32 v34, v128, v129
	v_cvt_pk_bf16_f32 v35, v46, v47
	s_waitcnt lgkmcnt(0)
	s_nop 0
	v_mfma_f32_32x32x16_bf16 v[0:15], v[38:41], v[32:35], v[0:15]
	ds_read2_b64 v[38:41], v96 offset0:76 offset1:78
	s_waitcnt lgkmcnt(0)
	v_mfma_f32_32x32x16_bf16 v[16:31], v[38:41], v[32:35], v[16:31]
	s_andn2_b64 exec, exec, s[12:13]
	s_cbranch_execz .LBB0_641
